# L2-locality tile remap (8x8 supertile per XCD) for gemm_p and gemm_up
# speedup vs baseline: 1.0147x; 1.0147x over previous
; __device__ __forceinline__ int tid_() { int x = threadIdx.x; asm volatile("" : "+v"(x)); return x; }
; __device__ __forceinline__ int bid_() { int x = blockIdx.x; asm volatile("" : "+s"(x)); return x; }
; __device__ __forceinline__ void gemm_acc2(const bf16_t* __restrict__ A, long lda, const bf16_t* __restrict__ Bt, long ldb, int K, f32x4 (&acc)[8][4], char* lds) {
;     const int tid = tid_(), wid = tid >> 6, lane = tid & 63, wr = wid >> 1, wc = wid & 1, fr = lane & 15, fq = lane >> 4;
;     const int nk = K >> 5;
;     gemm2_stage(A, lda, Bt, ldb, 0, lds, tid);
;     asm volatile("s_waitcnt vmcnt(0)" ::: "memory");
;     __syncthreads();
; __device__ void ph_gemm_up(const Params& P, char* lds) {
;     ...
;     for (int item = bid_(); item < 128 * 44; item += gridDim.x) {
;         const int mt = item / 44, nt = item % 44;
;         f32x4 acc[8][4]; zero_acc2(acc);
.LBB0_290:
	v_readlane_b32 s1, v239, 10
	s_mov_b32 s26, s21
	s_cmp_lg_u32 s1, 0x200
	s_cbranch_scc1 .Lmy_up_noperm
	s_or_b32 s1, s21, 0x1ff
	s_cmpk_gt_i32 s1, 0x15ff
	s_cbranch_scc1 .Lmy_up_noperm
	s_and_b32 s26, s21, 7
	s_lshl_b32 s26, s26, 6
	s_bfe_u32 s1, s21, 0x60003
	s_or_b32 s26, s26, s1
	s_andn2_b32 s1, s21, 0x1ff
	s_or_b32 s26, s26, s1
.Lmy_up_noperm:
	s_mul_hi_u32 s0, s26, 0xba2e8c
	s_mulk_i32 s0, 0x160
	s_sub_i32 s1, s26, s0
	s_mul_hi_u32 s0, s26, 0xba2e8c
	s_and_b32 s44, s1, 7
	s_lshl_b32 s0, s0, 3
	s_add_i32 s44, s44, s0
	s_lshr_b32 s0, s1, 3
	s_mov_b32 s45, 0
	s_waitcnt vmcnt(10)
	v_mov_b32_e32 v14, v178
	v_lshrrev_b32_e32 v15, 4, v14
	s_lshl_b64 s[48:49], s[44:45], 19
	v_readlane_b32 s26, v241, 31
	v_xor_b32_e32 v0, v15, v14
	v_readlane_b32 s27, v241, 32
	s_add_u32 s26, s26, s48
	v_lshlrev_b32_e32 v142, 4, v14
	v_lshlrev_b32_e32 v0, 4, v0
	v_ashrrev_i32_e32 v4, 2, v14
	s_addc_u32 s27, s27, s49
	s_ashr_i32 s1, s0, 31
	v_and_b32_e32 v0, 48, v0
	v_ashrrev_i32_e32 v5, 31, v4
	v_add_u32_e32 v16, 0, v142
	s_lshl_b64 s[28:29], s[0:1], 18
	v_lshl_add_u64 v[2:3], s[26:27], 0, v[0:1]
	v_lshlrev_b64 v[4:5], 11, v[4:5]
	v_readfirstlane_b32 s1, v16
	v_lshl_add_u64 v[6:7], v[2:3], 0, v[4:5]
	s_mov_b32 m0, s1
	v_add_u32_e32 v10, 0x1000, v16
	global_load_lds_dwordx4 v[6:7], off
	v_add_u32_e32 v6, 0x1000, v142
	v_ashrrev_i32_e32 v6, 6, v6
	v_ashrrev_i32_e32 v7, 31, v6
	v_lshlrev_b64 v[6:7], 11, v[6:7]
	v_readfirstlane_b32 s1, v10
	v_lshl_add_u64 v[8:9], v[2:3], 0, v[6:7]
	s_mov_b32 m0, s1
	v_add_u32_e32 v12, 0x2000, v16
	global_load_lds_dwordx4 v[8:9], off
	v_add_u32_e32 v8, 0x2000, v142
	v_ashrrev_i32_e32 v8, 6, v8
	v_ashrrev_i32_e32 v9, 31, v8
	v_lshlrev_b64 v[8:9], 11, v[8:9]
	v_readfirstlane_b32 s1, v12
	v_lshl_add_u64 v[10:11], v[2:3], 0, v[8:9]
	s_mov_b32 m0, s1
	v_readlane_b32 s50, v241, 39
	global_load_lds_dwordx4 v[10:11], off
	v_add_u32_e32 v10, 0x3000, v142
	v_ashrrev_i32_e32 v10, 6, v10
	v_ashrrev_i32_e32 v11, 31, v10
	v_add_u32_e32 v12, 0x3000, v16
	v_readlane_b32 s51, v241, 40
	s_add_u32 s50, s50, s28
	v_lshlrev_b64 v[10:11], 11, v[10:11]
	v_readfirstlane_b32 s1, v12
	s_addc_u32 s51, s51, s29
	v_lshl_add_u64 v[2:3], v[2:3], 0, v[10:11]
	s_mov_b32 m0, s1
	v_readlane_b32 s26, v239, 49
	global_load_lds_dwordx4 v[2:3], off
	v_lshl_add_u64 v[2:3], s[50:51], 0, v[0:1]
	v_add_u32_e32 v0, 0x4000, v16
	v_lshl_add_u64 v[12:13], v[2:3], 0, v[4:5]
	v_readfirstlane_b32 s1, v0
	v_add_u32_e32 v0, 0x5000, v16
	s_mov_b32 m0, s1
	v_readfirstlane_b32 s1, v0
	global_load_lds_dwordx4 v[12:13], off
	v_lshl_add_u64 v[2:3], v[2:3], 0, v[6:7]
	s_mov_b32 m0, s1
	v_bitop3_b32 v12, v15, 3, v14 bitop3:0x48
	global_load_lds_dwordx4 v[2:3], off
	v_lshl_add_u64 v[2:3], s[48:49], 0, v[4:5]
	v_lshlrev_b32_e32 v12, 4, v12
	v_or_b32_e32 v2, v2, v12
	v_readlane_b32 s27, v239, 50
	v_lshrrev_b32_e32 v0, 2, v14
	v_xor_b32_e32 v0, v15, v0
	v_lshl_add_u64 v[130:131], s[26:27], 0, v[2:3]
	v_lshl_add_u64 v[2:3], s[48:49], 0, v[6:7]
	v_or_b32_e32 v2, v2, v12
	v_lshl_add_u64 v[132:133], s[26:27], 0, v[2:3]
	v_lshl_add_u64 v[2:3], s[48:49], 0, v[8:9]
	v_or_b32_e32 v2, v2, v12
	v_lshl_add_u64 v[134:135], s[26:27], 0, v[2:3]
	v_lshl_add_u64 v[2:3], s[48:49], 0, v[10:11]
	v_or_b32_e32 v2, v2, v12
	v_lshl_add_u64 v[136:137], s[26:27], 0, v[2:3]
	v_lshl_add_u64 v[2:3], s[28:29], 0, v[4:5]
	v_readlane_b32 s26, v239, 51
	v_or_b32_e32 v2, v2, v12
	v_readlane_b32 s27, v239, 52
	s_waitcnt vmcnt(0)
	v_lshlrev_b32_e32 v0, 4, v0
	v_and_b32_e32 v143, 48, v0
	v_lshl_add_u64 v[138:139], s[26:27], 0, v[2:3]
	v_lshl_add_u64 v[2:3], s[28:29], 0, v[6:7]
	v_or_b32_e32 v2, v2, v12
	v_lshlrev_b32_e32 v0, 6, v14
	v_lshl_add_u64 v[140:141], s[26:27], 0, v[2:3]
	v_mov_b32_e32 v2, 0
	v_and_b32_e32 v144, 0x13c0, v0
	v_and_b32_e32 v0, 0xffffe3c0, v0
	v_add_u32_e32 v145, 0, v143
	s_mov_b64 s[48:49], 0
	s_mov_b32 s1, 1
	v_mov_b32_e32 v3, v2
	v_mov_b32_e32 v4, v2
	v_mov_b32_e32 v5, v2
	v_mov_b32_e32 v6, v2
	v_mov_b32_e32 v7, v2
	v_mov_b32_e32 v8, v2
	v_mov_b32_e32 v9, v2
	v_mov_b32_e32 v10, v2
	v_mov_b32_e32 v11, v2
	v_mov_b32_e32 v12, v2
	v_mov_b32_e32 v13, v2
	v_mov_b32_e32 v14, v2
	v_mov_b32_e32 v15, v2
	v_mov_b32_e32 v16, v2
	v_mov_b32_e32 v17, v2
	s_waitcnt vmcnt(0)
	v_mov_b32_e32 v18, v2
	v_mov_b32_e32 v19, v2
	v_mov_b32_e32 v20, v2
	v_mov_b32_e32 v21, v2
	v_mov_b32_e32 v22, v2
	v_mov_b32_e32 v23, v2
	v_mov_b32_e32 v24, v2
	v_mov_b32_e32 v25, v2
	v_mov_b32_e32 v26, v2
	v_mov_b32_e32 v27, v2
	v_mov_b32_e32 v28, v2
	v_mov_b32_e32 v29, v2
	v_mov_b32_e32 v30, v2
	v_mov_b32_e32 v31, v2
	v_mov_b32_e32 v32, v2
	v_mov_b32_e32 v33, v2
	v_mov_b32_e32 v34, v2
	v_mov_b32_e32 v35, v2
	v_mov_b32_e32 v36, v2
	v_mov_b32_e32 v37, v2
	v_mov_b32_e32 v38, v2
	v_mov_b32_e32 v39, v2
	v_mov_b32_e32 v40, v2
	v_mov_b32_e32 v41, v2
	v_mov_b32_e32 v42, v2
	v_mov_b32_e32 v43, v2
	v_mov_b32_e32 v44, v2
	v_mov_b32_e32 v45, v2
	v_mov_b32_e32 v46, v2
	v_mov_b32_e32 v47, v2
	v_mov_b32_e32 v48, v2
	v_mov_b32_e32 v49, v2
	v_mov_b32_e32 v50, v2
	v_mov_b32_e32 v51, v2
	v_mov_b32_e32 v52, v2
	v_mov_b32_e32 v53, v2
	v_mov_b32_e32 v54, v2
	v_mov_b32_e32 v55, v2
	v_mov_b32_e32 v56, v2
	v_mov_b32_e32 v57, v2
	v_mov_b32_e32 v58, v2
	v_mov_b32_e32 v59, v2
	v_mov_b32_e32 v60, v2
	v_mov_b32_e32 v61, v2
	v_mov_b32_e32 v62, v2
	v_mov_b32_e32 v63, v2
	v_mov_b32_e32 v64, v2
	v_mov_b32_e32 v65, v2
	v_mov_b32_e32 v66, v2
	v_mov_b32_e32 v67, v2
	v_mov_b32_e32 v68, v2
	v_mov_b32_e32 v69, v2
	v_mov_b32_e32 v70, v2
	v_mov_b32_e32 v71, v2
	v_mov_b32_e32 v72, v2
	v_mov_b32_e32 v73, v2
	v_mov_b32_e32 v74, v2
	v_mov_b32_e32 v75, v2
	v_mov_b32_e32 v76, v2
	v_mov_b32_e32 v77, v2
	v_mov_b32_e32 v78, v2
	v_mov_b32_e32 v79, v2
	v_mov_b32_e32 v80, v2
	v_mov_b32_e32 v81, v2
	v_mov_b32_e32 v82, v2
	v_mov_b32_e32 v83, v2
	v_mov_b32_e32 v84, v2
	v_mov_b32_e32 v85, v2
	v_mov_b32_e32 v86, v2
	v_mov_b32_e32 v87, v2
	v_mov_b32_e32 v88, v2
	v_mov_b32_e32 v89, v2
	v_mov_b32_e32 v90, v2
	v_mov_b32_e32 v91, v2
	v_mov_b32_e32 v92, v2
	v_mov_b32_e32 v93, v2
	v_mov_b32_e32 v94, v2
	v_mov_b32_e32 v95, v2
	v_mov_b32_e32 v96, v2
	v_mov_b32_e32 v97, v2
	v_mov_b32_e32 v98, v2
	v_mov_b32_e32 v99, v2
	v_mov_b32_e32 v100, v2
	v_mov_b32_e32 v101, v2
	v_mov_b32_e32 v102, v2
	v_mov_b32_e32 v103, v2
	v_mov_b32_e32 v104, v2
	v_mov_b32_e32 v105, v2
	v_mov_b32_e32 v106, v2
	v_mov_b32_e32 v107, v2
	v_mov_b32_e32 v108, v2
	v_mov_b32_e32 v109, v2
	v_mov_b32_e32 v110, v2
	v_mov_b32_e32 v111, v2
	v_mov_b32_e32 v112, v2
	v_mov_b32_e32 v113, v2
	v_mov_b32_e32 v114, v2
	v_mov_b32_e32 v115, v2
	v_mov_b32_e32 v116, v2
	v_mov_b32_e32 v117, v2
	v_mov_b32_e32 v118, v2
	v_mov_b32_e32 v119, v2
	v_mov_b32_e32 v120, v2
	v_mov_b32_e32 v121, v2
	v_mov_b32_e32 v122, v2
	v_mov_b32_e32 v123, v2
	v_mov_b32_e32 v124, v2
	v_mov_b32_e32 v125, v2
	v_mov_b32_e32 v126, v2
	v_mov_b32_e32 v127, v2
	v_mov_b32_e32 v128, v2
	v_mov_b32_e32 v129, v2
	s_waitcnt vmcnt(0) lgkmcnt(0)
	s_barrier

; __device__ __forceinline__ int tid_() { int x = threadIdx.x; asm volatile("" : "+v"(x)); return x; }
; __device__ __forceinline__ int bid_() { int x = blockIdx.x; asm volatile("" : "+s"(x)); return x; }
; __device__ __forceinline__ void gemm_acc2(const bf16_t* __restrict__ A, long lda, const bf16_t* __restrict__ Bt, long ldb, int K, f32x4 (&acc)[8][4], char* lds) {
;     const int tid = tid_(), wid = tid >> 6, lane = tid & 63, wr = wid >> 1, wc = wid & 1, fr = lane & 15, fq = lane >> 4;
;     const int nk = K >> 5;
;     gemm2_stage(A, lda, Bt, ldb, 0, lds, tid);
;     asm volatile("s_waitcnt vmcnt(0)" ::: "memory");
;     __syncthreads();
; __device__ void ph_gemm_p(const Params& P, char* lds) {
;     ...
;     for (int item = bid_(); item < 128 * 55; item += gridDim.x) {
;         const int mt = item / 55, nt = item % 55;
;         f32x4 acc[8][4]; zero_acc2(acc);
;         gemm_acc2(U + (size_t)mt * 256 * DM, DM, Wt + (size_t)nt * 128 * DM, DM, DM, acc, lds);
.LBB0_451:
	v_readlane_b32 s1, v239, 10
	s_mov_b32 s38, s21
	s_cmp_lg_u32 s1, 0x200
	s_cbranch_scc1 .Lmy_p_noperm
	s_or_b32 s1, s21, 0x1ff
	s_cmpk_gt_i32 s1, 0x1b7f
	s_cbranch_scc1 .Lmy_p_noperm
	s_and_b32 s38, s21, 7
	s_lshl_b32 s38, s38, 6
	s_bfe_u32 s1, s21, 0x60003
	s_or_b32 s38, s38, s1
	s_andn2_b32 s1, s21, 0x1ff
	s_or_b32 s38, s38, s1
.Lmy_p_noperm:
	s_mul_hi_u32 s0, s38, 0x94f20a
	s_mul_i32 s1, s0, 0x1b8
	s_sub_i32 s1, s38, s1
	s_lshr_b32 s38, s1, 3
	s_and_b32 s1, s1, 7
	s_lshl_b32 s0, s0, 3
	s_add_i32 s0, s0, s1
	s_mov_b32 s1, 0
	s_waitcnt vmcnt(10)
	v_mov_b32_e32 v14, v178
	s_lshl_b64 s[42:43], s[0:1], 19
	v_lshrrev_b32_e32 v15, 4, v14
	v_readlane_b32 s26, v241, 31
	v_xor_b32_e32 v0, v15, v14
	v_readlane_b32 s27, v241, 32
	s_add_u32 s26, s26, s42
	v_lshlrev_b32_e32 v142, 4, v14
	v_lshlrev_b32_e32 v0, 4, v0
	v_ashrrev_i32_e32 v4, 2, v14
	s_addc_u32 s27, s27, s43
	v_and_b32_e32 v0, 48, v0
	v_ashrrev_i32_e32 v5, 31, v4
	v_add_u32_e32 v16, 0, v142
	v_lshl_add_u64 v[2:3], s[26:27], 0, v[0:1]
	v_lshlrev_b64 v[4:5], 11, v[4:5]
	v_readfirstlane_b32 s1, v16
	v_lshl_add_u64 v[6:7], v[2:3], 0, v[4:5]
	s_mov_b32 m0, s1
	v_add_u32_e32 v10, 0x1000, v16
	global_load_lds_dwordx4 v[6:7], off
	v_add_u32_e32 v6, 0x1000, v142
	v_ashrrev_i32_e32 v6, 6, v6
	v_ashrrev_i32_e32 v7, 31, v6
	v_lshlrev_b64 v[6:7], 11, v[6:7]
	v_readfirstlane_b32 s1, v10
	v_lshl_add_u64 v[8:9], v[2:3], 0, v[6:7]
	s_mov_b32 m0, s1
	v_add_u32_e32 v12, 0x2000, v16
	global_load_lds_dwordx4 v[8:9], off
	v_add_u32_e32 v8, 0x2000, v142
	v_ashrrev_i32_e32 v8, 6, v8
	v_ashrrev_i32_e32 v9, 31, v8
	v_lshlrev_b64 v[8:9], 11, v[8:9]
	v_readfirstlane_b32 s1, v12
	v_lshl_add_u64 v[10:11], v[2:3], 0, v[8:9]
	s_mov_b32 m0, s1
	s_ashr_i32 s39, s38, 31
	global_load_lds_dwordx4 v[10:11], off
	v_add_u32_e32 v10, 0x3000, v142
	v_ashrrev_i32_e32 v10, 6, v10
	s_lshl_b64 s[28:29], s[38:39], 18
	v_ashrrev_i32_e32 v11, 31, v10
	v_add_u32_e32 v12, 0x3000, v16
	s_add_u32 s44, s74, s28
	v_lshlrev_b64 v[10:11], 11, v[10:11]
	v_readfirstlane_b32 s1, v12
	s_addc_u32 s45, s75, s29
	v_lshl_add_u64 v[2:3], v[2:3], 0, v[10:11]
	s_mov_b32 m0, s1
	v_readlane_b32 s26, v239, 49
	global_load_lds_dwordx4 v[2:3], off
	v_lshl_add_u64 v[2:3], s[44:45], 0, v[0:1]
	v_add_u32_e32 v0, 0x4000, v16
	v_lshl_add_u64 v[12:13], v[2:3], 0, v[4:5]
	v_readfirstlane_b32 s1, v0
	v_add_u32_e32 v0, 0x5000, v16
	s_mov_b32 m0, s1
	v_readfirstlane_b32 s1, v0
	global_load_lds_dwordx4 v[12:13], off
	v_lshl_add_u64 v[2:3], v[2:3], 0, v[6:7]
	s_mov_b32 m0, s1
	v_bitop3_b32 v12, v15, 3, v14 bitop3:0x48
	global_load_lds_dwordx4 v[2:3], off
	v_lshl_add_u64 v[2:3], s[42:43], 0, v[4:5]
	v_lshlrev_b32_e32 v12, 4, v12
	v_or_b32_e32 v2, v2, v12
	v_readlane_b32 s27, v239, 50
	v_lshrrev_b32_e32 v0, 2, v14
	v_xor_b32_e32 v0, v15, v0
	v_lshl_add_u64 v[130:131], s[26:27], 0, v[2:3]
	v_lshl_add_u64 v[2:3], s[42:43], 0, v[6:7]
	v_or_b32_e32 v2, v2, v12
	v_lshl_add_u64 v[132:133], s[26:27], 0, v[2:3]
	v_lshl_add_u64 v[2:3], s[42:43], 0, v[8:9]
	v_or_b32_e32 v2, v2, v12
	v_lshl_add_u64 v[134:135], s[26:27], 0, v[2:3]
	v_lshl_add_u64 v[2:3], s[42:43], 0, v[10:11]
	v_or_b32_e32 v2, v2, v12
	v_lshl_add_u64 v[136:137], s[26:27], 0, v[2:3]
	v_lshl_add_u64 v[2:3], s[28:29], 0, v[4:5]
	v_readlane_b32 s26, v239, 63
	v_or_b32_e32 v2, v2, v12
	v_readlane_b32 s27, v238, 0
	s_waitcnt vmcnt(0)
	v_lshlrev_b32_e32 v0, 4, v0
	v_and_b32_e32 v143, 48, v0
	v_lshl_add_u64 v[138:139], s[26:27], 0, v[2:3]
	v_lshl_add_u64 v[2:3], s[28:29], 0, v[6:7]
	v_or_b32_e32 v2, v2, v12
	v_lshlrev_b32_e32 v0, 6, v14
	v_lshl_add_u64 v[140:141], s[26:27], 0, v[2:3]
	v_mov_b32_e32 v2, 0
	s_mov_b32 s24, 1
	v_and_b32_e32 v144, 0x13c0, v0
	v_and_b32_e32 v0, 0xffffe3c0, v0
	v_add_u32_e32 v145, 0, v143
	s_mov_b64 s[42:43], 0
	v_mov_b32_e32 v3, v2
	v_mov_b32_e32 v4, v2
	v_mov_b32_e32 v5, v2
	v_mov_b32_e32 v6, v2
	v_mov_b32_e32 v7, v2
	v_mov_b32_e32 v8, v2
	v_mov_b32_e32 v9, v2
	v_mov_b32_e32 v10, v2
	v_mov_b32_e32 v11, v2
	v_mov_b32_e32 v12, v2
	v_mov_b32_e32 v13, v2
	v_mov_b32_e32 v14, v2
	v_mov_b32_e32 v15, v2
	v_mov_b32_e32 v16, v2
	v_mov_b32_e32 v17, v2
	s_waitcnt vmcnt(0)
	v_mov_b32_e32 v18, v2
	v_mov_b32_e32 v19, v2
	v_mov_b32_e32 v20, v2
	v_mov_b32_e32 v21, v2
	v_mov_b32_e32 v22, v2
	v_mov_b32_e32 v23, v2
	v_mov_b32_e32 v24, v2
	v_mov_b32_e32 v25, v2
	v_mov_b32_e32 v26, v2
	v_mov_b32_e32 v27, v2
	v_mov_b32_e32 v28, v2
	v_mov_b32_e32 v29, v2
	v_mov_b32_e32 v30, v2
	v_mov_b32_e32 v31, v2
	v_mov_b32_e32 v32, v2
	v_mov_b32_e32 v33, v2
	v_mov_b32_e32 v34, v2
	v_mov_b32_e32 v35, v2
	v_mov_b32_e32 v36, v2
	v_mov_b32_e32 v37, v2
	v_mov_b32_e32 v38, v2
	v_mov_b32_e32 v39, v2
	v_mov_b32_e32 v40, v2
	v_mov_b32_e32 v41, v2
	v_mov_b32_e32 v42, v2
	v_mov_b32_e32 v43, v2
	v_mov_b32_e32 v44, v2
	v_mov_b32_e32 v45, v2
	v_mov_b32_e32 v46, v2
	v_mov_b32_e32 v47, v2
	v_mov_b32_e32 v48, v2
	v_mov_b32_e32 v49, v2
	v_mov_b32_e32 v50, v2
	v_mov_b32_e32 v51, v2
	v_mov_b32_e32 v52, v2
	v_mov_b32_e32 v53, v2
	v_mov_b32_e32 v54, v2
	v_mov_b32_e32 v55, v2
	v_mov_b32_e32 v56, v2
	v_mov_b32_e32 v57, v2
	v_mov_b32_e32 v58, v2
	v_mov_b32_e32 v59, v2
	v_mov_b32_e32 v60, v2
	v_mov_b32_e32 v61, v2
	v_mov_b32_e32 v62, v2
	v_mov_b32_e32 v63, v2
	v_mov_b32_e32 v64, v2
	v_mov_b32_e32 v65, v2
	v_mov_b32_e32 v66, v2
	v_mov_b32_e32 v67, v2
	v_mov_b32_e32 v68, v2
	v_mov_b32_e32 v69, v2
	v_mov_b32_e32 v70, v2
	v_mov_b32_e32 v71, v2
	v_mov_b32_e32 v72, v2
	v_mov_b32_e32 v73, v2
	v_mov_b32_e32 v74, v2
	v_mov_b32_e32 v75, v2
	v_mov_b32_e32 v76, v2
	v_mov_b32_e32 v77, v2
	v_mov_b32_e32 v78, v2
	v_mov_b32_e32 v79, v2
	v_mov_b32_e32 v80, v2
	v_mov_b32_e32 v81, v2
	v_mov_b32_e32 v82, v2
	v_mov_b32_e32 v83, v2
	v_mov_b32_e32 v84, v2
	v_mov_b32_e32 v85, v2
	v_mov_b32_e32 v86, v2
	v_mov_b32_e32 v87, v2
	v_mov_b32_e32 v88, v2
	v_mov_b32_e32 v89, v2
	v_mov_b32_e32 v90, v2
	v_mov_b32_e32 v91, v2
	v_mov_b32_e32 v92, v2
	v_mov_b32_e32 v93, v2
	v_mov_b32_e32 v94, v2
	v_mov_b32_e32 v95, v2
	v_mov_b32_e32 v96, v2
	v_mov_b32_e32 v97, v2
	v_mov_b32_e32 v98, v2
	v_mov_b32_e32 v99, v2
	v_mov_b32_e32 v100, v2
	v_mov_b32_e32 v101, v2
	v_mov_b32_e32 v102, v2
	v_mov_b32_e32 v103, v2
	v_mov_b32_e32 v104, v2
	v_mov_b32_e32 v105, v2
	v_mov_b32_e32 v106, v2
	v_mov_b32_e32 v107, v2
	v_mov_b32_e32 v108, v2
	v_mov_b32_e32 v109, v2
	v_mov_b32_e32 v110, v2
	v_mov_b32_e32 v111, v2
	v_mov_b32_e32 v112, v2
	v_mov_b32_e32 v113, v2
	v_mov_b32_e32 v114, v2
	v_mov_b32_e32 v115, v2
	v_mov_b32_e32 v116, v2
	v_mov_b32_e32 v117, v2
	v_mov_b32_e32 v118, v2
	v_mov_b32_e32 v119, v2
	v_mov_b32_e32 v120, v2
	v_mov_b32_e32 v121, v2
	v_mov_b32_e32 v122, v2
	v_mov_b32_e32 v123, v2
	v_mov_b32_e32 v124, v2
	v_mov_b32_e32 v125, v2
	v_mov_b32_e32 v126, v2
	v_mov_b32_e32 v127, v2
	v_mov_b32_e32 v128, v2
	v_mov_b32_e32 v129, v2
	s_waitcnt vmcnt(0) lgkmcnt(0)
	s_barrier
